# FoX tile loop: active waves stage the next tile into LDS right after the scale/gate FMAs instead of after the PV MFMAs
# baseline (speedup 1.0000x reference)
.LBB0_180:
	s_cmp_lt_i32 s7, 0
	s_cbranch_scc1 .Lfx_eve_sk
	s_and_b64 vcc, exec, s[48:49]
	s_cbranch_vccnz .Lfx_eve_w0
	s_waitcnt vmcnt(3)
	s_branch .Lfx_eve_st

; template <int MODE> ...
;     ...
;             for (int r = 1; r < 15; r += 2) { mx = max3f(mx, s1[r], s0[r + 1]); mx = max3f(mx, s1[r + 1], (r + 2 < 16) ? s0[r + 2] : s1[r + 1]); }
;             mx = fmaxf(mx, s1[15]);
;             mx = half_max(mx);
;             const bool minf = (m == -INFINITY);
;             if (__any((mx > RESC_THR) || (minf && mx > -INFINITY))) {
;                 const float delta = minf ? ((mx == -INFINITY) ? 0.f : mx) : fmaxf(mx, 0.f);
;                 m = (minf && mx == -INFINITY) ? -INFINITY : mref + delta;
;                 { const float nm = (m == -INFINITY) ? 0.f : -m * (1.0f / SC2);
; #pragma unroll
;                   for (int r = 0; r < 16; ++r) negm[r] = nm; }
;                 const float alpha = minf ? 1.f : ex2(-delta);
;                 l *= alpha;
;                 if (MODE != MODE_CMP1) { o[0] = o[0] * alpha; o[1] = o[1] * alpha; }
; #pragma unroll
;                 for (int r = 0; r < 16; ++r) { s0[r] -= delta; s1[r] -= delta; }
;             }
;             float ps = 0.f;
; #pragma unroll
;             for (int r = 0; r < 16; ++r) { s0[r] = ex2(s0[r]); s1[r] = ex2(s1[r]); ps += s0[r] + s1[r]; }
;             l += ps;
;         } else {
; #pragma unroll
;             for (int r = 0; r < 16; ++r) { s0[r] = ex2(s0[r]) * linv; s1[r] = ex2(s1[r]) * linv; }
;             float quad[8], last[8], recv[8];
; #pragma unroll
;             for (int a = 0; a < 4; ++a) {
;                 quad[a] = (s0[4 * a] + s0[4 * a + 1]) + (s0[4 * a + 2] + s0[4 * a + 3]); last[a] = s0[4 * a + 3];
;                 quad[4 + a] = (s1[4 * a] + s1[4 * a + 1]) + (s1[4 * a + 2] + s1[4 * a + 3]); last[4 + a] = s1[4 * a + 3];
;             }
; #pragma unroll
;             for (int i = 0; i < 8; ++i) recv[i] = half_other(last[i], hl);
; #pragma unroll
;             for (int i = 0; i < 8; ++i) {
;                 const float prev = (i > 0) ? recv[i > 0 ? i - 1 : 0] : carry;
;                 float v = quad[i] + (hl ? recv[i] : prev);
;                 v += __shfl_xor(v, 1); v += __shfl_xor(v, 2);
;                 if ((n & 3) == 0) lds_st<float>(L + score_ofs + (16 * kt + 2 * i + hl) * 4, v);
;             }
;             carry = recv[7];
;         }
;         if (MODE != MODE_CMP1) {
;             bf16x8 pf[4];
; #pragma unroll
;             for (int ks = 0; ks < 4; ++ks) {
;                 const int hb = 8 * (ks & 1); u32x4 w;
.Lfx_eve_st:
	ds_write_b128 v129, v[112:115] offset:9216
	ds_write_b128 v131, v[116:119] offset:30720
	s_and_saveexec_b64 s[0:1], s[38:39]
	ds_write_b32 v132, v130 offset:43264
	s_or_b64 exec, exec, s[0:1]
.Lfx_eve_sk:
	v_cmp_eq_f32_e64 s[0:1], s16, v142
	v_max3_f32 v0, v80, v64, v81
	v_max3_f32 v90, v72, v89, v73
	v_max3_f32 v0, v0, v65, v82
	v_max3_f32 v90, v90, v14, v74
	v_max3_f32 v0, v0, v66, v83
	v_max3_f32 v90, v90, v15, v75
	v_max3_f32 v0, v0, v67, v84
	v_max3_f32 v90, v90, v12, v76
	v_max3_f32 v0, v0, v68, v85
	v_max3_f32 v90, v90, v13, v77
	v_max3_f32 v0, v0, v69, v86
	v_max3_f32 v90, v90, v10, v78
	v_max3_f32 v0, v0, v70, v87
	v_max3_f32 v90, v90, v11, v79
	v_max3_f32 v0, v0, v71, v88
	v_max_f32_e32 v0, v0, v0
	v_max_f32_e32 v0, v0, v90
	v_mov_b32_e32 v90, v0
	s_nop 1
	v_permlane32_swap_b32_e32 v0, v90
	v_max_f32_e32 v90, v90, v90
	v_max_f32_e32 v0, v0, v0
	v_max_f32_e32 v0, v0, v90
	v_cmp_lg_f32_e64 s[40:41], s16, v0
	v_cmp_lt_f32_e32 vcc, s17, v0
	s_and_b64 s[40:41], s[0:1], s[40:41]
	s_or_b64 vcc, vcc, s[40:41]
	s_cbranch_vccz .LBB0_182
	v_cmp_eq_f32_e32 vcc, s16, v0
	v_cndmask_b32_e64 v48, v142, 0, s[0:1]
	s_nop 0
	v_cndmask_b32_e64 v49, v0, 0, vcc
	v_max_f32_e32 v0, v0, v0
	v_max_f32_e32 v0, 0, v0
	v_cndmask_b32_e64 v0, v0, v49, s[0:1]
	v_exp_f32_e64 v90, -v0
	v_add_f32_e32 v48, v48, v0
	s_and_b64 vcc, s[0:1], vcc
	v_cndmask_b32_e32 v142, v48, v220, vcc
	v_mul_f32_e32 v48, 0xc0b17218, v142
	v_cmp_neq_f32_e32 vcc, s16, v142
	v_cndmask_b32_e64 v90, v90, 1.0, s[0:1]
	v_mul_f32_e32 v140, v140, v90
	v_cndmask_b32_e32 v48, 0, v48, vcc
	v_mov_b32_e32 v49, v48
	v_mov_b32_e32 v50, v48
	v_mov_b32_e32 v51, v48
	v_mov_b32_e32 v52, v48
	v_mov_b32_e32 v53, v48
	v_mov_b32_e32 v54, v48
	v_mov_b32_e32 v55, v48
	v_mov_b32_e32 v56, v48
	v_mov_b32_e32 v57, v48
	v_mov_b32_e32 v58, v48
	v_mov_b32_e32 v59, v48
	v_mov_b32_e32 v60, v48
	v_mov_b32_e32 v61, v48
	v_mov_b32_e32 v62, v48
	v_mov_b32_e32 v63, v48
	v_pk_mul_f32 v[46:47], v[46:47], v[90:91] op_sel_hi:[1,0]
	v_pk_mul_f32 v[44:45], v[44:45], v[90:91] op_sel_hi:[1,0]
	v_pk_mul_f32 v[42:43], v[42:43], v[90:91] op_sel_hi:[1,0]
	v_pk_mul_f32 v[40:41], v[40:41], v[90:91] op_sel_hi:[1,0]
	v_pk_mul_f32 v[38:39], v[38:39], v[90:91] op_sel_hi:[1,0]
	v_pk_mul_f32 v[36:37], v[36:37], v[90:91] op_sel_hi:[1,0]
	v_pk_mul_f32 v[34:35], v[34:35], v[90:91] op_sel_hi:[1,0]
	v_pk_mul_f32 v[32:33], v[32:33], v[90:91] op_sel_hi:[1,0]
	v_pk_mul_f32 v[30:31], v[30:31], v[90:91] op_sel_hi:[1,0]
	v_pk_mul_f32 v[28:29], v[28:29], v[90:91] op_sel_hi:[1,0]
	v_pk_mul_f32 v[26:27], v[26:27], v[90:91] op_sel_hi:[1,0]
	v_pk_mul_f32 v[24:25], v[24:25], v[90:91] op_sel_hi:[1,0]
	v_pk_mul_f32 v[22:23], v[22:23], v[90:91] op_sel_hi:[1,0]
	v_pk_mul_f32 v[20:21], v[20:21], v[90:91] op_sel_hi:[1,0]
	v_pk_mul_f32 v[18:19], v[18:19], v[90:91] op_sel_hi:[1,0]
	v_pk_mul_f32 v[16:17], v[16:17], v[90:91] op_sel_hi:[1,0]
	v_pk_add_f32 v[80:81], v[80:81], v[0:1] op_sel_hi:[1,0] neg_lo:[0,1] neg_hi:[0,1]
	v_pk_add_f32 v[64:65], v[64:65], v[0:1] op_sel_hi:[1,0] neg_lo:[0,1] neg_hi:[0,1]
	v_pk_add_f32 v[82:83], v[82:83], v[0:1] op_sel_hi:[1,0] neg_lo:[0,1] neg_hi:[0,1]
	v_pk_add_f32 v[66:67], v[66:67], v[0:1] op_sel_hi:[1,0] neg_lo:[0,1] neg_hi:[0,1]
	v_pk_add_f32 v[84:85], v[84:85], v[0:1] op_sel_hi:[1,0] neg_lo:[0,1] neg_hi:[0,1]
	v_pk_add_f32 v[68:69], v[68:69], v[0:1] op_sel_hi:[1,0] neg_lo:[0,1] neg_hi:[0,1]
	v_pk_add_f32 v[86:87], v[86:87], v[0:1] op_sel_hi:[1,0] neg_lo:[0,1] neg_hi:[0,1]
	v_pk_add_f32 v[70:71], v[70:71], v[0:1] op_sel_hi:[1,0] neg_lo:[0,1] neg_hi:[0,1]
	v_pk_add_f32 v[88:89], v[88:89], v[0:1] op_sel_hi:[1,0] neg_lo:[0,1] neg_hi:[0,1]
	v_pk_add_f32 v[72:73], v[72:73], v[0:1] op_sel_hi:[1,0] neg_lo:[0,1] neg_hi:[0,1]
	v_pk_add_f32 v[14:15], v[14:15], v[0:1] op_sel_hi:[1,0] neg_lo:[0,1] neg_hi:[0,1]
	v_pk_add_f32 v[74:75], v[74:75], v[0:1] op_sel_hi:[1,0] neg_lo:[0,1] neg_hi:[0,1]
	v_pk_add_f32 v[12:13], v[12:13], v[0:1] op_sel_hi:[1,0] neg_lo:[0,1] neg_hi:[0,1]
	v_pk_add_f32 v[76:77], v[76:77], v[0:1] op_sel_hi:[1,0] neg_lo:[0,1] neg_hi:[0,1]
	v_pk_add_f32 v[10:11], v[10:11], v[0:1] op_sel_hi:[1,0] neg_lo:[0,1] neg_hi:[0,1]
	v_pk_add_f32 v[78:79], v[78:79], v[0:1] op_sel_hi:[1,0] neg_lo:[0,1] neg_hi:[0,1]
.LBB0_182:
	s_waitcnt lgkmcnt(0)
	v_exp_f32_e32 v80, v80
	v_exp_f32_e32 v81, v81
	v_exp_f32_e32 v82, v82
	v_exp_f32_e32 v83, v83
	v_exp_f32_e32 v84, v84
	v_exp_f32_e32 v85, v85
	v_exp_f32_e32 v86, v86
	v_exp_f32_e32 v87, v87
	v_cvt_pk_bf16_f32 v170, v80, v81
	v_cvt_pk_bf16_f32 v171, v82, v83
	v_pk_add_f32 v[186:187], v[80:81], v[82:83]
	v_cvt_pk_bf16_f32 v172, v84, v85
	v_cvt_pk_bf16_f32 v173, v86, v87
	v_pk_add_f32 v[188:189], v[84:85], v[86:87]
	v_exp_f32_e32 v88, v88
	v_exp_f32_e32 v89, v89
	v_exp_f32_e32 v14, v14
	v_exp_f32_e32 v15, v15
	v_mfma_f32_32x32x16_bf16 v[16:31], v[206:209], v[170:173], v[16:31]
	v_exp_f32_e32 v12, v12
	v_exp_f32_e32 v13, v13
	v_exp_f32_e32 v10, v10
	v_exp_f32_e32 v11, v11
	v_mfma_f32_32x32x16_bf16 v[32:47], v[234:237], v[170:173], v[32:47]
	v_cvt_pk_bf16_f32 v174, v88, v89
	v_pk_add_f32 v[186:187], v[186:187], v[88:89]
	v_cvt_pk_bf16_f32 v175, v14, v15
	v_pk_add_f32 v[188:189], v[188:189], v[14:15]
	v_cvt_pk_bf16_f32 v176, v12, v13
	v_pk_add_f32 v[186:187], v[186:187], v[12:13]
	v_cvt_pk_bf16_f32 v177, v10, v11
	v_pk_add_f32 v[188:189], v[188:189], v[10:11]
	v_exp_f32_e32 v64, v64
	v_exp_f32_e32 v65, v65
	v_exp_f32_e32 v66, v66
	v_exp_f32_e32 v67, v67
	v_mfma_f32_32x32x16_bf16 v[16:31], v[210:213], v[174:177], v[16:31]
	v_exp_f32_e32 v68, v68
	v_exp_f32_e32 v69, v69
	v_exp_f32_e32 v70, v70
	v_exp_f32_e32 v71, v71
	v_mfma_f32_32x32x16_bf16 v[32:47], v[238:241], v[174:177], v[32:47]
	v_cvt_pk_bf16_f32 v178, v64, v65
	v_pk_add_f32 v[186:187], v[186:187], v[64:65]
	v_cvt_pk_bf16_f32 v179, v66, v67
	v_pk_add_f32 v[188:189], v[188:189], v[66:67]
	v_cvt_pk_bf16_f32 v180, v68, v69
	v_pk_add_f32 v[186:187], v[186:187], v[68:69]
	v_cvt_pk_bf16_f32 v181, v70, v71
	v_pk_add_f32 v[188:189], v[188:189], v[70:71]
	v_exp_f32_e32 v72, v72
	v_exp_f32_e32 v73, v73
	v_exp_f32_e32 v74, v74
	v_exp_f32_e32 v75, v75
	v_mfma_f32_32x32x16_bf16 v[16:31], v[226:229], v[178:181], v[16:31]
	v_exp_f32_e32 v76, v76
	v_exp_f32_e32 v77, v77
	v_exp_f32_e32 v78, v78
	v_exp_f32_e32 v79, v79
	v_mfma_f32_32x32x16_bf16 v[32:47], v[242:245], v[178:181], v[32:47]
	v_cvt_pk_bf16_f32 v182, v72, v73
	v_pk_add_f32 v[186:187], v[186:187], v[72:73]
	v_cvt_pk_bf16_f32 v183, v74, v75
	v_pk_add_f32 v[188:189], v[188:189], v[74:75]
	v_cvt_pk_bf16_f32 v184, v76, v77
	v_pk_add_f32 v[186:187], v[186:187], v[76:77]
	v_cvt_pk_bf16_f32 v185, v78, v79
	v_pk_add_f32 v[188:189], v[188:189], v[78:79]
	v_pk_add_f32 v[186:187], v[186:187], v[188:189]
	s_nop 0
	v_add_f32_e32 v186, v186, v187
	v_mfma_f32_32x32x16_bf16 v[16:31], v[230:233], v[182:185], v[16:31]
	v_add_f32_e32 v140, v140, v186
	v_mfma_f32_32x32x16_bf16 v[32:47], v[246:249], v[182:185], v[32:47]
	s_or_b64 exec, exec, s[56:57]
	s_branch .LBB0_186

.LBB0_196:
	s_andn2_b64 vcc, exec, s[50:51]
	s_cbranch_vccnz .Lfx_ode_sk
	s_and_b64 vcc, exec, s[56:57]
	s_cbranch_vccnz .Lfx_ode_w0
	s_waitcnt vmcnt(3)
	s_branch .Lfx_ode_st

.Lfx_ode_st:
	ds_write_b128 v129, v[6:9]
	ds_write_b128 v131, v[2:5] offset:18432
	s_and_saveexec_b64 s[0:1], s[38:39]
	ds_write_b32 v132, v141 offset:43008
	s_or_b64 exec, exec, s[0:1]

; template <int MODE> ...
;     ...
;             float ps = 0.f;
; #pragma unroll
;             for (int r = 0; r < 16; ++r) { s0[r] = ex2(s0[r]); s1[r] = ex2(s1[r]); ps += s0[r] + s1[r]; }
;             l += ps;
;         } else {
; #pragma unroll
;             for (int r = 0; r < 16; ++r) { s0[r] = ex2(s0[r]) * linv; s1[r] = ex2(s1[r]) * linv; }
;             float quad[8], last[8], recv[8];
; #pragma unroll
;             for (int a = 0; a < 4; ++a) {
;                 quad[a] = (s0[4 * a] + s0[4 * a + 1]) + (s0[4 * a + 2] + s0[4 * a + 3]); last[a] = s0[4 * a + 3];
;                 quad[4 + a] = (s1[4 * a] + s1[4 * a + 1]) + (s1[4 * a + 2] + s1[4 * a + 3]); last[4 + a] = s1[4 * a + 3];
;             }
; #pragma unroll
;             for (int i = 0; i < 8; ++i) recv[i] = half_other(last[i], hl);
; #pragma unroll
;             for (int i = 0; i < 8; ++i) {
;                 const float prev = (i > 0) ? recv[i > 0 ? i - 1 : 0] : carry;
;                 float v = quad[i] + (hl ? recv[i] : prev);
;                 v += __shfl_xor(v, 1); v += __shfl_xor(v, 2);
;                 if ((n & 3) == 0) lds_st<float>(L + score_ofs + (16 * kt + 2 * i + hl) * 4, v);
;             }
;             carry = recv[7];
;         }
;         if (MODE != MODE_CMP1) {
;             bf16x8 pf[4];
; #pragma unroll
;             for (int ks = 0; ks < 4; ++ks) {
;                 const int hb = 8 * (ks & 1); u32x4 w;
;                 if (ks >> 1) { w.x = cvt_pk(s1[hb], s1[hb + 1]); w.y = cvt_pk(s1[hb + 2], s1[hb + 3]); w.z = cvt_pk(s1[hb + 4], s1[hb + 5]); w.w = cvt_pk(s1[hb + 6], s1[hb + 7]); }
;                 else { w.x = cvt_pk(s0[hb], s0[hb + 1]); w.y = cvt_pk(s0[hb + 2], s0[hb + 3]); w.z = cvt_pk(s0[hb + 4], s0[hb + 5]); w.w = cvt_pk(s0[hb + 6], s0[hb + 7]); }
;                 pf[ks] = __builtin_bit_cast(bf16x8, w);
;             }
;             const lptr vb_ = Vt + (4 * hl + q4) * VP + 32 * blk + 8 * p4;
; #pragma unroll
;             for (int c_ = 0; c_ < 2; ++c_)
; #pragma unroll
;                 for (int ks_ = 0; ks_ < 4; ++ks_) {
;                     const s16x4 lo_ = tr16(vb_ + (16 * ks_) * VP + 64 * c_), hi_ = tr16(vb_ + (16 * ks_ + 8) * VP + 64 * c_);
;                     const bf16x8 vf_ = {lo_[0], lo_[1], lo_[2], lo_[3], hi_[0], hi_[1], hi_[2], hi_[3]};
;                     o[c_] = mfma32(vf_, pf[ks_], o[c_]);
;                 }
.LBB0_198:
	s_waitcnt lgkmcnt(0)
	v_exp_f32_e32 v80, v80
	v_exp_f32_e32 v81, v81
	v_exp_f32_e32 v82, v82
	v_exp_f32_e32 v83, v83
	v_exp_f32_e32 v84, v84
	v_exp_f32_e32 v85, v85
	v_exp_f32_e32 v86, v86
	v_exp_f32_e32 v87, v87
	v_cvt_pk_bf16_f32 v170, v80, v81
	v_cvt_pk_bf16_f32 v171, v82, v83
	v_pk_add_f32 v[186:187], v[80:81], v[82:83]
	v_cvt_pk_bf16_f32 v172, v84, v85
	v_cvt_pk_bf16_f32 v173, v86, v87
	v_pk_add_f32 v[188:189], v[84:85], v[86:87]
	v_exp_f32_e32 v88, v88
	v_exp_f32_e32 v89, v89
	v_exp_f32_e32 v14, v14
	v_exp_f32_e32 v15, v15
	v_mfma_f32_32x32x16_bf16 v[16:31], v[206:209], v[170:173], v[16:31]
	v_exp_f32_e32 v12, v12
	v_exp_f32_e32 v13, v13
	v_exp_f32_e32 v10, v10
	v_exp_f32_e32 v11, v11
	v_mfma_f32_32x32x16_bf16 v[32:47], v[234:237], v[170:173], v[32:47]
	v_cvt_pk_bf16_f32 v174, v88, v89
	v_pk_add_f32 v[186:187], v[186:187], v[88:89]
	v_cvt_pk_bf16_f32 v175, v14, v15
	v_pk_add_f32 v[188:189], v[188:189], v[14:15]
	v_cvt_pk_bf16_f32 v176, v12, v13
	v_pk_add_f32 v[186:187], v[186:187], v[12:13]
	v_cvt_pk_bf16_f32 v177, v10, v11
	v_pk_add_f32 v[188:189], v[188:189], v[10:11]
	v_exp_f32_e32 v64, v64
	v_exp_f32_e32 v65, v65
	v_exp_f32_e32 v66, v66
	v_exp_f32_e32 v67, v67
	v_mfma_f32_32x32x16_bf16 v[16:31], v[210:213], v[174:177], v[16:31]
	v_exp_f32_e32 v68, v68
	v_exp_f32_e32 v69, v69
	v_exp_f32_e32 v70, v70
	v_exp_f32_e32 v71, v71
	v_mfma_f32_32x32x16_bf16 v[32:47], v[238:241], v[174:177], v[32:47]
	v_cvt_pk_bf16_f32 v178, v64, v65
	v_pk_add_f32 v[186:187], v[186:187], v[64:65]
	v_cvt_pk_bf16_f32 v179, v66, v67
	v_pk_add_f32 v[188:189], v[188:189], v[66:67]
	v_cvt_pk_bf16_f32 v180, v68, v69
	v_pk_add_f32 v[186:187], v[186:187], v[68:69]
	v_cvt_pk_bf16_f32 v181, v70, v71
	v_pk_add_f32 v[188:189], v[188:189], v[70:71]
	v_exp_f32_e32 v72, v72
	v_exp_f32_e32 v73, v73
	v_exp_f32_e32 v74, v74
	v_exp_f32_e32 v75, v75
	v_mfma_f32_32x32x16_bf16 v[16:31], v[226:229], v[178:181], v[16:31]
	v_exp_f32_e32 v76, v76
	v_exp_f32_e32 v77, v77
	v_exp_f32_e32 v78, v78
	v_exp_f32_e32 v79, v79
	v_mfma_f32_32x32x16_bf16 v[32:47], v[242:245], v[178:181], v[32:47]
	v_cvt_pk_bf16_f32 v182, v72, v73
	v_pk_add_f32 v[186:187], v[186:187], v[72:73]
	v_cvt_pk_bf16_f32 v183, v74, v75
	v_pk_add_f32 v[188:189], v[188:189], v[74:75]
	v_cvt_pk_bf16_f32 v184, v76, v77
	v_pk_add_f32 v[186:187], v[186:187], v[76:77]
	v_cvt_pk_bf16_f32 v185, v78, v79
	v_pk_add_f32 v[188:189], v[188:189], v[78:79]
	v_pk_add_f32 v[186:187], v[186:187], v[188:189]
	s_nop 0
	v_add_f32_e32 v186, v186, v187
	v_mfma_f32_32x32x16_bf16 v[16:31], v[230:233], v[182:185], v[16:31]
	v_add_f32_e32 v140, v140, v186
	v_mfma_f32_32x32x16_bf16 v[32:47], v[246:249], v[182:185], v[32:47]
	s_or_b64 exec, exec, s[58:59]
	s_branch .LBB0_171
